# fin H-recompute de-serialised: tile-invariant scale/shift/gamma/beta hoisted, 8 row loads + 8 stats loads batched, counted vmcnt
# speedup vs baseline: 1.0376x; 1.0053x over previous
.LBB0_370:
	s_lshl_b64 s[16:17], s[96:97], 10
	s_add_u32 s2, s12, s16
	v_mov_b32_e32 v28, v254
	s_addc_u32 s16, s13, s17
	s_lshl_b64 s[20:21], s[6:7], 1
	s_barrier
	s_add_u32 s22, s2, s20
	v_lshrrev_b32_e32 v29, 2, v28
	v_and_b32_e32 v29, 0x1fffffec, v29
	s_movk_i32 s2, 0x88
	v_and_b32_e32 v28, 0x4f, v28
	v_mul_lo_u32 v29, v29, s2
	v_add_lshl_u32 v28, v29, v28, 1
	ds_read_u16 v29, v28 offset:36864
	ds_read_u16 v30, v28 offset:36896
	s_addc_u32 s23, s16, s21
	s_cmpk_lt_i32 s83, 0x80
	s_mov_b32 s2, 0
	s_waitcnt lgkmcnt(1)
	v_lshlrev_b32_e32 v29, 16, v29
	v_mul_f32_e32 v29, v32, v29
	v_cvt_pk_bf16_f32 v29, v29, s0
	ds_write_b16 v28, v29
	ds_read_u16 v29, v28 offset:37136
	s_waitcnt lgkmcnt(0)
	v_lshlrev_b32_e32 v29, 16, v29
	v_mul_f32_e32 v29, v33, v29
	v_cvt_pk_bf16_f32 v29, v29, s0
	ds_write_b16 v28, v29 offset:272
	ds_read_u16 v29, v28 offset:37408
	s_waitcnt lgkmcnt(0)
	v_lshlrev_b32_e32 v29, 16, v29
	v_mul_f32_e32 v29, v34, v29
	v_cvt_pk_bf16_f32 v29, v29, s0
	ds_write_b16 v28, v29 offset:544
	ds_read_u16 v29, v28 offset:37680
	s_waitcnt lgkmcnt(0)
	v_lshlrev_b32_e32 v29, 16, v29
	v_mul_f32_e32 v29, v35, v29
	v_cvt_pk_bf16_f32 v29, v29, s0
	ds_write_b16 v28, v29 offset:816
	v_lshlrev_b32_e32 v29, 16, v30
	v_mul_f32_e32 v24, v24, v29
	v_cvt_pk_bf16_f32 v24, v24, s0
	ds_write_b16 v28, v24 offset:32
	ds_read_u16 v24, v28 offset:37168
	s_waitcnt lgkmcnt(0)
	v_lshlrev_b32_e32 v24, 16, v24
	v_mul_f32_e32 v24, v25, v24
	v_cvt_pk_bf16_f32 v24, v24, s0
	ds_write_b16 v28, v24 offset:304
	ds_read_u16 v24, v28 offset:37440
	s_waitcnt lgkmcnt(0)
	v_lshlrev_b32_e32 v24, 16, v24
	v_mul_f32_e32 v24, v26, v24
	v_cvt_pk_bf16_f32 v24, v24, s0
	ds_write_b16 v28, v24 offset:576
	ds_read_u16 v24, v28 offset:37712
	s_waitcnt lgkmcnt(0)
	v_lshlrev_b32_e32 v24, 16, v24
	v_mul_f32_e32 v24, v27, v24
	v_cvt_pk_bf16_f32 v24, v24, s0
	ds_write_b16 v28, v24 offset:848
	ds_read_u16 v24, v28 offset:36928
	ds_read_u16 v25, v28 offset:36960
	s_waitcnt lgkmcnt(1)
	v_lshlrev_b32_e32 v24, 16, v24
	v_mul_f32_e32 v20, v20, v24
	v_cvt_pk_bf16_f32 v20, v20, s0
	ds_write_b16 v28, v20 offset:64
	ds_read_u16 v20, v28 offset:37200
	s_waitcnt lgkmcnt(0)
	v_lshlrev_b32_e32 v20, 16, v20
	v_mul_f32_e32 v20, v21, v20
	v_cvt_pk_bf16_f32 v20, v20, s0
	ds_write_b16 v28, v20 offset:336
	ds_read_u16 v20, v28 offset:37472
	s_waitcnt lgkmcnt(0)
	v_lshlrev_b32_e32 v20, 16, v20
	v_mul_f32_e32 v20, v22, v20
	v_cvt_pk_bf16_f32 v20, v20, s0
	ds_write_b16 v28, v20 offset:608
	ds_read_u16 v20, v28 offset:37744
	s_waitcnt lgkmcnt(0)
	v_lshlrev_b32_e32 v20, 16, v20
	v_mul_f32_e32 v20, v23, v20
	v_cvt_pk_bf16_f32 v20, v20, s0
	ds_write_b16 v28, v20 offset:880
	v_lshlrev_b32_e32 v20, 16, v25
	v_mul_f32_e32 v16, v16, v20
	v_cvt_pk_bf16_f32 v16, v16, s0
	ds_write_b16 v28, v16 offset:96
	ds_read_u16 v16, v28 offset:37232
	s_waitcnt lgkmcnt(0)
	v_lshlrev_b32_e32 v16, 16, v16
	v_mul_f32_e32 v16, v17, v16
	v_cvt_pk_bf16_f32 v16, v16, s0
	ds_write_b16 v28, v16 offset:368
	ds_read_u16 v16, v28 offset:37504
	s_waitcnt lgkmcnt(0)
	v_lshlrev_b32_e32 v16, 16, v16
	v_mul_f32_e32 v16, v18, v16
	v_cvt_pk_bf16_f32 v16, v16, s0
	ds_write_b16 v28, v16 offset:640
	ds_read_u16 v16, v28 offset:37776
	s_waitcnt lgkmcnt(0)
	v_lshlrev_b32_e32 v16, 16, v16
	v_mul_f32_e32 v16, v19, v16
	v_cvt_pk_bf16_f32 v16, v16, s0
	ds_write_b16 v28, v16 offset:912
	ds_read_u16 v16, v28 offset:41216
	s_waitcnt lgkmcnt(0)
	v_lshlrev_b32_e32 v16, 16, v16
	v_mul_f32_e32 v12, v12, v16
	v_cvt_pk_bf16_f32 v12, v12, s0
	ds_write_b16 v28, v12 offset:4352
	ds_read_u16 v12, v28 offset:41488
	s_waitcnt lgkmcnt(0)
	v_lshlrev_b32_e32 v12, 16, v12
	v_mul_f32_e32 v12, v13, v12
	v_cvt_pk_bf16_f32 v12, v12, s0
	ds_write_b16 v28, v12 offset:4624
	ds_read_u16 v12, v28 offset:41760
	s_waitcnt lgkmcnt(0)
	v_lshlrev_b32_e32 v12, 16, v12
	v_mul_f32_e32 v12, v14, v12
	v_cvt_pk_bf16_f32 v12, v12, s0
	ds_write_b16 v28, v12 offset:4896
	ds_read_u16 v12, v28 offset:42032
	s_waitcnt lgkmcnt(0)
	v_lshlrev_b32_e32 v12, 16, v12
	v_mul_f32_e32 v12, v15, v12
	v_cvt_pk_bf16_f32 v12, v12, s0
	ds_write_b16 v28, v12 offset:5168
	ds_read_u16 v12, v28 offset:41248
	s_waitcnt lgkmcnt(0)
	v_lshlrev_b32_e32 v12, 16, v12
	v_mul_f32_e32 v8, v8, v12
	v_cvt_pk_bf16_f32 v8, v8, s0
	ds_write_b16 v28, v8 offset:4384
	ds_read_u16 v8, v28 offset:41520
	s_waitcnt lgkmcnt(0)
	v_lshlrev_b32_e32 v8, 16, v8
	v_mul_f32_e32 v8, v9, v8
	v_cvt_pk_bf16_f32 v8, v8, s0
	ds_write_b16 v28, v8 offset:4656
	ds_read_u16 v8, v28 offset:41792
	s_waitcnt lgkmcnt(0)
	v_lshlrev_b32_e32 v8, 16, v8
	v_mul_f32_e32 v8, v10, v8
	v_cvt_pk_bf16_f32 v8, v8, s0
	ds_write_b16 v28, v8 offset:4928
	ds_read_u16 v8, v28 offset:42064
	s_waitcnt lgkmcnt(0)
	v_lshlrev_b32_e32 v8, 16, v8
	v_mul_f32_e32 v8, v11, v8
	v_cvt_pk_bf16_f32 v8, v8, s0
	ds_write_b16 v28, v8 offset:5200
	ds_read_u16 v8, v28 offset:41280
	s_waitcnt lgkmcnt(0)
	v_lshlrev_b32_e32 v8, 16, v8
	v_mul_f32_e32 v4, v4, v8
	v_cvt_pk_bf16_f32 v4, v4, s0
	ds_write_b16 v28, v4 offset:4416
	ds_read_u16 v4, v28 offset:41552
	v_mov_b32_e32 v8, v254
	s_waitcnt lgkmcnt(0)
	v_lshlrev_b32_e32 v4, 16, v4
	v_mul_f32_e32 v4, v5, v4
	v_cvt_pk_bf16_f32 v4, v4, s0
	ds_write_b16 v28, v4 offset:4688
	ds_read_u16 v4, v28 offset:41824
	s_waitcnt lgkmcnt(0)
	v_lshlrev_b32_e32 v4, 16, v4
	v_mul_f32_e32 v4, v6, v4
	v_cvt_pk_bf16_f32 v4, v4, s0
	ds_write_b16 v28, v4 offset:4960
	ds_read_u16 v4, v28 offset:42096
	s_waitcnt lgkmcnt(0)
	v_lshlrev_b32_e32 v4, 16, v4
	v_mul_f32_e32 v4, v7, v4
	v_cvt_pk_bf16_f32 v4, v4, s0
	ds_write_b16 v28, v4 offset:5232
	ds_read_u16 v4, v28 offset:41312
	s_waitcnt lgkmcnt(0)
	v_lshlrev_b32_e32 v4, 16, v4
	v_mul_f32_e32 v0, v0, v4
	v_cvt_pk_bf16_f32 v0, v0, s0
	ds_write_b16 v28, v0 offset:4448
	ds_read_u16 v0, v28 offset:41584
	s_waitcnt lgkmcnt(0)
	v_lshlrev_b32_e32 v0, 16, v0
	v_mul_f32_e32 v0, v1, v0
	v_cvt_pk_bf16_f32 v0, v0, s0
	ds_write_b16 v28, v0 offset:4720
	ds_read_u16 v0, v28 offset:41856
	s_waitcnt lgkmcnt(0)
	v_lshlrev_b32_e32 v0, 16, v0
	v_mul_f32_e32 v0, v2, v0
	v_cvt_pk_bf16_f32 v0, v0, s0
	ds_write_b16 v28, v0 offset:4992
	ds_read_u16 v0, v28 offset:42128
	s_waitcnt lgkmcnt(0)
	v_lshlrev_b32_e32 v0, 16, v0
	v_mul_f32_e32 v0, v3, v0
	v_cvt_pk_bf16_f32 v0, v0, s0
	ds_write_b16 v28, v0 offset:5264
	s_waitcnt lgkmcnt(0)
	s_barrier
	s_nop 0
	v_lshlrev_b32_e32 v0, 4, v8
	v_and_b32_e32 v148, 0xf0, v0
	v_ashrrev_i32_e32 v6, 4, v8
	v_mad_u64_u32 v[0:1], s[16:17], v6, s42, v[148:149]
	ds_read_b128 v[0:3], v0
	v_ashrrev_i32_e32 v7, 31, v6
	v_lshl_add_u64 v[4:5], s[22:23], 0, v[148:149]
	v_lshlrev_b64 v[6:7], 10, v[6:7]
	v_lshl_add_u64 v[6:7], v[4:5], 0, v[6:7]
	s_waitcnt lgkmcnt(0)
	global_store_dwordx4 v[6:7], v[0:3], off
	s_nop 1
	v_add_u32_e32 v0, 0x100, v8
	v_ashrrev_i32_e32 v6, 4, v0
	v_mad_u64_u32 v[0:1], s[16:17], v6, s42, v[148:149]
	ds_read_b128 v[0:3], v0
	v_ashrrev_i32_e32 v7, 31, v6
	v_lshlrev_b64 v[6:7], 10, v[6:7]
	v_lshl_add_u64 v[6:7], v[4:5], 0, v[6:7]
	s_waitcnt lgkmcnt(0)
	global_store_dwordx4 v[6:7], v[0:3], off
	s_nop 1
	v_add_u32_e32 v0, 0x200, v8
	v_ashrrev_i32_e32 v6, 4, v0
	v_mad_u64_u32 v[0:1], s[16:17], v6, s42, v[148:149]
	ds_read_b128 v[0:3], v0
	v_ashrrev_i32_e32 v7, 31, v6
	v_lshlrev_b64 v[6:7], 10, v[6:7]
	v_lshl_add_u64 v[6:7], v[4:5], 0, v[6:7]
	s_waitcnt lgkmcnt(0)
	global_store_dwordx4 v[6:7], v[0:3], off
	s_nop 1
	v_add_u32_e32 v0, 0x300, v8
	v_ashrrev_i32_e32 v6, 4, v0
	v_mad_u64_u32 v[0:1], s[16:17], v6, s42, v[148:149]
	ds_read_b128 v[0:3], v0
	s_cselect_b64 s[16:17], -1, 0
	s_add_i32 s7, s96, 0xffffe000
	s_and_b64 s[22:23], s[16:17], exec
	v_ashrrev_i32_e32 v7, 31, v6
	s_cselect_b32 s25, s96, s7
	s_cselect_b32 s33, s97, 0
	s_cselect_b32 s46, 0, 8
	s_and_b64 s[22:23], s[90:91], exec
	v_lshlrev_b64 v[6:7], 10, v[6:7]
	s_cselect_b32 s22, s25, s96
	s_cselect_b32 s25, s46, 0x118
	v_lshl_add_u64 v[4:5], v[4:5], 0, v[6:7]
	s_cselect_b32 s23, s33, s97
	s_add_u32 s98, s8, s25
	s_waitcnt lgkmcnt(0)
	global_store_dwordx4 v[4:5], v[0:3], off
	s_addc_u32 s99, s9, 0
	s_load_dwordx2 s[98:99], s[98:99], 0x0
	s_lshl_b64 s[22:23], s[22:23], 12
	v_add_u32_e32 v4, s6, v82
	v_ashrrev_i32_e32 v5, 31, v4
	v_lshlrev_b64 v[4:5], 2, v[4:5]
	s_waitcnt lgkmcnt(0)
	s_add_u32 s22, s98, s22
	s_addc_u32 s23, s99, s23
	s_lshr_b32 s7, s7, 11
	s_add_i32 s7, s7, 1
	s_and_b64 s[16:17], s[16:17], exec
	s_cselect_b32 s7, 0, s7
	s_mul_i32 s16, s82, 9
	s_add_i32 s7, s7, s16
	s_mul_hi_u32 s17, s7, 0x6000
	s_mulk_i32 s7, 0x6000
	s_add_u32 s16, s10, s7
	s_addc_u32 s17, s11, s17
	v_lshl_add_u64 v[8:9], s[16:17], 0, v[4:5]
	s_mov_b64 s[6:7], 0x1000
	v_lshl_add_u64 v[0:1], v[58:59], 0, s[20:21]
	v_lshl_add_u64 v[2:3], v[60:61], 0, s[20:21]
	v_lshl_add_u64 v[6:7], s[22:23], 0, v[4:5]
	v_lshl_add_u64 v[10:11], v[8:9], 0, s[6:7]
	global_load_dwordx4 v[104:107], v[10:11], off
	global_load_dwordx4 v[108:111], v[10:11], off offset:16
	global_load_dwordx4 v[112:115], v[8:9], off
	global_load_dwordx4 v[116:119], v[8:9], off offset:16
	s_and_b64 vcc, exec, s[92:93]
	s_cbranch_vccz .Lfh_l0
	s_load_dwordx4 s[20:23], s[8:9], 0x108
	s_waitcnt lgkmcnt(0)
	v_lshl_add_u64 v[12:13], s[20:21], 0, v[4:5]
	v_lshl_add_u64 v[14:15], s[22:23], 0, v[4:5]
	global_load_dwordx4 v[120:123], v[12:13], off
	global_load_dwordx4 v[124:127], v[12:13], off offset:16
	global_load_dwordx4 v[128:131], v[14:15], off
	global_load_dwordx4 v[132:135], v[14:15], off offset:16
	v_ashrrev_i32_e32 v12, 5, v57
	v_ashrrev_i32_e32 v13, 31, v12
	v_lshl_add_u64 v[16:17], v[12:13], 0, s[96:97]
	v_lshlrev_b64 v[14:15], 12, v[12:13]
	v_lshl_add_u64 v[14:15], v[6:7], 0, v[14:15]
	s_mov_b64 s[6:7], 0x8000
	v_lshl_add_u64 v[18:19], v[16:17], 3, s[94:95]
	global_load_dwordx2 v[230:231], v[18:19], off
	global_load_dwordx2 v[232:233], v[18:19], off offset:64
	global_load_dwordx2 v[234:235], v[18:19], off offset:128
	global_load_dwordx2 v[236:237], v[18:19], off offset:192
	global_load_dwordx2 v[238:239], v[18:19], off offset:256
	global_load_dwordx2 v[240:241], v[18:19], off offset:320
	global_load_dwordx2 v[242:243], v[18:19], off offset:384
	global_load_dwordx2 v[244:245], v[18:19], off offset:448
	global_load_dwordx4 v[166:169], v[14:15], off
	global_load_dwordx4 v[170:173], v[14:15], off offset:16
	v_lshl_add_u64 v[14:15], v[14:15], 0, s[6:7]
	global_load_dwordx4 v[174:177], v[14:15], off
	global_load_dwordx4 v[178:181], v[14:15], off offset:16
	v_lshl_add_u64 v[14:15], v[14:15], 0, s[6:7]
	global_load_dwordx4 v[182:185], v[14:15], off
	global_load_dwordx4 v[186:189], v[14:15], off offset:16
	v_lshl_add_u64 v[14:15], v[14:15], 0, s[6:7]
	global_load_dwordx4 v[190:193], v[14:15], off
	global_load_dwordx4 v[194:197], v[14:15], off offset:16
	v_lshl_add_u64 v[14:15], v[14:15], 0, s[6:7]
	global_load_dwordx4 v[198:201], v[14:15], off
	global_load_dwordx4 v[202:205], v[14:15], off offset:16
	v_lshl_add_u64 v[14:15], v[14:15], 0, s[6:7]
	global_load_dwordx4 v[206:209], v[14:15], off
	global_load_dwordx4 v[210:213], v[14:15], off offset:16
	v_lshl_add_u64 v[14:15], v[14:15], 0, s[6:7]
	global_load_dwordx4 v[214:217], v[14:15], off
	global_load_dwordx4 v[218:221], v[14:15], off offset:16
	v_lshl_add_u64 v[14:15], v[14:15], 0, s[6:7]
	global_load_dwordx4 v[222:225], v[14:15], off
	global_load_dwordx4 v[226:229], v[14:15], off offset:16
	v_lshlrev_b64 v[16:17], 10, v[16:17]
	v_lshl_add_u64 v[30:31], v[2:3], 0, v[16:17]
	v_lshl_add_u64 v[32:33], v[0:1], 0, v[16:17]
	v_lshl_add_u64 v[32:33], v[32:33], 0, s[78:79]
	v_cndmask_b32_e64 v33, v33, v31, s[4:5]
	v_cndmask_b32_e64 v32, v32, v30, s[4:5]
	s_mov_b64 s[6:7], 0x2000
	s_waitcnt vmcnt(14)
	v_pk_add_f32 v[136:137], v[104:105], 1.0 op_sel_hi:[1,0]
	v_pk_add_f32 v[138:139], v[106:107], 1.0 op_sel_hi:[1,0]
	v_pk_add_f32 v[140:141], v[108:109], 1.0 op_sel_hi:[1,0]
	v_pk_add_f32 v[142:143], v[110:111], 1.0 op_sel_hi:[1,0]
	v_pk_add_f32 v[18:19], v[166:167], v[230:231] op_sel_hi:[1,0] neg_lo:[0,1] neg_hi:[0,1]
	v_pk_add_f32 v[20:21], v[168:169], v[230:231] op_sel_hi:[1,0] neg_lo:[0,1] neg_hi:[0,1]
	v_pk_add_f32 v[22:23], v[170:171], v[230:231] op_sel_hi:[1,0] neg_lo:[0,1] neg_hi:[0,1]
	v_pk_add_f32 v[24:25], v[172:173], v[230:231] op_sel_hi:[1,0] neg_lo:[0,1] neg_hi:[0,1]
	v_pk_mul_f32 v[18:19], v[230:231], v[18:19] op_sel:[1,0]
	v_pk_mul_f32 v[20:21], v[230:231], v[20:21] op_sel:[1,0]
	v_pk_mul_f32 v[22:23], v[230:231], v[22:23] op_sel:[1,0]
	v_pk_mul_f32 v[24:25], v[230:231], v[24:25] op_sel:[1,0]
	v_pk_fma_f32 v[18:19], v[120:121], v[18:19], v[128:129]
	v_pk_fma_f32 v[20:21], v[122:123], v[20:21], v[130:131]
	v_pk_fma_f32 v[22:23], v[124:125], v[22:23], v[132:133]
	v_pk_fma_f32 v[24:25], v[126:127], v[24:25], v[134:135]
	v_pk_fma_f32 v[18:19], v[18:19], v[136:137], v[112:113]
	v_pk_fma_f32 v[20:21], v[20:21], v[138:139], v[114:115]
	v_pk_fma_f32 v[22:23], v[22:23], v[140:141], v[116:117]
	v_pk_fma_f32 v[24:25], v[24:25], v[142:143], v[118:119]
	v_cvt_pk_bf16_f32 v26, v18, v19
	v_cvt_pk_bf16_f32 v27, v20, v21
	v_cvt_pk_bf16_f32 v28, v22, v23
	v_cvt_pk_bf16_f32 v29, v24, v25
	global_store_dwordx4 v[32:33], v[26:29], off
	v_lshl_add_u64 v[32:33], v[32:33], 0, s[6:7]
	s_waitcnt vmcnt(13)
	v_pk_add_f32 v[18:19], v[174:175], v[232:233] op_sel_hi:[1,0] neg_lo:[0,1] neg_hi:[0,1]
	v_pk_add_f32 v[20:21], v[176:177], v[232:233] op_sel_hi:[1,0] neg_lo:[0,1] neg_hi:[0,1]
	v_pk_add_f32 v[22:23], v[178:179], v[232:233] op_sel_hi:[1,0] neg_lo:[0,1] neg_hi:[0,1]
	v_pk_add_f32 v[24:25], v[180:181], v[232:233] op_sel_hi:[1,0] neg_lo:[0,1] neg_hi:[0,1]
	v_pk_mul_f32 v[18:19], v[232:233], v[18:19] op_sel:[1,0]
	v_pk_mul_f32 v[20:21], v[232:233], v[20:21] op_sel:[1,0]
	v_pk_mul_f32 v[22:23], v[232:233], v[22:23] op_sel:[1,0]
	v_pk_mul_f32 v[24:25], v[232:233], v[24:25] op_sel:[1,0]
	v_pk_fma_f32 v[18:19], v[120:121], v[18:19], v[128:129]
	v_pk_fma_f32 v[20:21], v[122:123], v[20:21], v[130:131]
	v_pk_fma_f32 v[22:23], v[124:125], v[22:23], v[132:133]
	v_pk_fma_f32 v[24:25], v[126:127], v[24:25], v[134:135]
	v_pk_fma_f32 v[18:19], v[18:19], v[136:137], v[112:113]
	v_pk_fma_f32 v[20:21], v[20:21], v[138:139], v[114:115]
	v_pk_fma_f32 v[22:23], v[22:23], v[140:141], v[116:117]
	v_pk_fma_f32 v[24:25], v[24:25], v[142:143], v[118:119]
	v_cvt_pk_bf16_f32 v144, v18, v19
	v_cvt_pk_bf16_f32 v145, v20, v21
	v_cvt_pk_bf16_f32 v146, v22, v23
	v_cvt_pk_bf16_f32 v147, v24, v25
	global_store_dwordx4 v[32:33], v[144:147], off
	v_lshl_add_u64 v[32:33], v[32:33], 0, s[6:7]
	s_waitcnt vmcnt(12)
	v_pk_add_f32 v[18:19], v[182:183], v[234:235] op_sel_hi:[1,0] neg_lo:[0,1] neg_hi:[0,1]
	v_pk_add_f32 v[20:21], v[184:185], v[234:235] op_sel_hi:[1,0] neg_lo:[0,1] neg_hi:[0,1]
	v_pk_add_f32 v[22:23], v[186:187], v[234:235] op_sel_hi:[1,0] neg_lo:[0,1] neg_hi:[0,1]
	v_pk_add_f32 v[24:25], v[188:189], v[234:235] op_sel_hi:[1,0] neg_lo:[0,1] neg_hi:[0,1]
	v_pk_mul_f32 v[18:19], v[234:235], v[18:19] op_sel:[1,0]
	v_pk_mul_f32 v[20:21], v[234:235], v[20:21] op_sel:[1,0]
	v_pk_mul_f32 v[22:23], v[234:235], v[22:23] op_sel:[1,0]
	v_pk_mul_f32 v[24:25], v[234:235], v[24:25] op_sel:[1,0]
	v_pk_fma_f32 v[18:19], v[120:121], v[18:19], v[128:129]
	v_pk_fma_f32 v[20:21], v[122:123], v[20:21], v[130:131]
	v_pk_fma_f32 v[22:23], v[124:125], v[22:23], v[132:133]
	v_pk_fma_f32 v[24:25], v[126:127], v[24:25], v[134:135]
	v_pk_fma_f32 v[18:19], v[18:19], v[136:137], v[112:113]
	v_pk_fma_f32 v[20:21], v[20:21], v[138:139], v[114:115]
	v_pk_fma_f32 v[22:23], v[22:23], v[140:141], v[116:117]
	v_pk_fma_f32 v[24:25], v[24:25], v[142:143], v[118:119]
	v_cvt_pk_bf16_f32 v26, v18, v19
	v_cvt_pk_bf16_f32 v27, v20, v21
	v_cvt_pk_bf16_f32 v28, v22, v23
	v_cvt_pk_bf16_f32 v29, v24, v25
	global_store_dwordx4 v[32:33], v[26:29], off
	v_lshl_add_u64 v[32:33], v[32:33], 0, s[6:7]
	s_waitcnt vmcnt(11)
	v_pk_add_f32 v[18:19], v[190:191], v[236:237] op_sel_hi:[1,0] neg_lo:[0,1] neg_hi:[0,1]
	v_pk_add_f32 v[20:21], v[192:193], v[236:237] op_sel_hi:[1,0] neg_lo:[0,1] neg_hi:[0,1]
	v_pk_add_f32 v[22:23], v[194:195], v[236:237] op_sel_hi:[1,0] neg_lo:[0,1] neg_hi:[0,1]
	v_pk_add_f32 v[24:25], v[196:197], v[236:237] op_sel_hi:[1,0] neg_lo:[0,1] neg_hi:[0,1]
	v_pk_mul_f32 v[18:19], v[236:237], v[18:19] op_sel:[1,0]
	v_pk_mul_f32 v[20:21], v[236:237], v[20:21] op_sel:[1,0]
	v_pk_mul_f32 v[22:23], v[236:237], v[22:23] op_sel:[1,0]
	v_pk_mul_f32 v[24:25], v[236:237], v[24:25] op_sel:[1,0]
	v_pk_fma_f32 v[18:19], v[120:121], v[18:19], v[128:129]
	v_pk_fma_f32 v[20:21], v[122:123], v[20:21], v[130:131]
	v_pk_fma_f32 v[22:23], v[124:125], v[22:23], v[132:133]
	v_pk_fma_f32 v[24:25], v[126:127], v[24:25], v[134:135]
	v_pk_fma_f32 v[18:19], v[18:19], v[136:137], v[112:113]
	v_pk_fma_f32 v[20:21], v[20:21], v[138:139], v[114:115]
	v_pk_fma_f32 v[22:23], v[22:23], v[140:141], v[116:117]
	v_pk_fma_f32 v[24:25], v[24:25], v[142:143], v[118:119]
	v_cvt_pk_bf16_f32 v144, v18, v19
	v_cvt_pk_bf16_f32 v145, v20, v21
	v_cvt_pk_bf16_f32 v146, v22, v23
	v_cvt_pk_bf16_f32 v147, v24, v25
	global_store_dwordx4 v[32:33], v[144:147], off
	v_lshl_add_u64 v[32:33], v[32:33], 0, s[6:7]
	s_waitcnt vmcnt(10)
	v_pk_add_f32 v[18:19], v[198:199], v[238:239] op_sel_hi:[1,0] neg_lo:[0,1] neg_hi:[0,1]
	v_pk_add_f32 v[20:21], v[200:201], v[238:239] op_sel_hi:[1,0] neg_lo:[0,1] neg_hi:[0,1]
	v_pk_add_f32 v[22:23], v[202:203], v[238:239] op_sel_hi:[1,0] neg_lo:[0,1] neg_hi:[0,1]
	v_pk_add_f32 v[24:25], v[204:205], v[238:239] op_sel_hi:[1,0] neg_lo:[0,1] neg_hi:[0,1]
	v_pk_mul_f32 v[18:19], v[238:239], v[18:19] op_sel:[1,0]
	v_pk_mul_f32 v[20:21], v[238:239], v[20:21] op_sel:[1,0]
	v_pk_mul_f32 v[22:23], v[238:239], v[22:23] op_sel:[1,0]
	v_pk_mul_f32 v[24:25], v[238:239], v[24:25] op_sel:[1,0]
	v_pk_fma_f32 v[18:19], v[120:121], v[18:19], v[128:129]
	v_pk_fma_f32 v[20:21], v[122:123], v[20:21], v[130:131]
	v_pk_fma_f32 v[22:23], v[124:125], v[22:23], v[132:133]
	v_pk_fma_f32 v[24:25], v[126:127], v[24:25], v[134:135]
	v_pk_fma_f32 v[18:19], v[18:19], v[136:137], v[112:113]
	v_pk_fma_f32 v[20:21], v[20:21], v[138:139], v[114:115]
	v_pk_fma_f32 v[22:23], v[22:23], v[140:141], v[116:117]
	v_pk_fma_f32 v[24:25], v[24:25], v[142:143], v[118:119]
	v_cvt_pk_bf16_f32 v26, v18, v19
	v_cvt_pk_bf16_f32 v27, v20, v21
	v_cvt_pk_bf16_f32 v28, v22, v23
	v_cvt_pk_bf16_f32 v29, v24, v25
	global_store_dwordx4 v[32:33], v[26:29], off
	v_lshl_add_u64 v[32:33], v[32:33], 0, s[6:7]
	s_waitcnt vmcnt(9)
	v_pk_add_f32 v[18:19], v[206:207], v[240:241] op_sel_hi:[1,0] neg_lo:[0,1] neg_hi:[0,1]
	v_pk_add_f32 v[20:21], v[208:209], v[240:241] op_sel_hi:[1,0] neg_lo:[0,1] neg_hi:[0,1]
	v_pk_add_f32 v[22:23], v[210:211], v[240:241] op_sel_hi:[1,0] neg_lo:[0,1] neg_hi:[0,1]
	v_pk_add_f32 v[24:25], v[212:213], v[240:241] op_sel_hi:[1,0] neg_lo:[0,1] neg_hi:[0,1]
	v_pk_mul_f32 v[18:19], v[240:241], v[18:19] op_sel:[1,0]
	v_pk_mul_f32 v[20:21], v[240:241], v[20:21] op_sel:[1,0]
	v_pk_mul_f32 v[22:23], v[240:241], v[22:23] op_sel:[1,0]
	v_pk_mul_f32 v[24:25], v[240:241], v[24:25] op_sel:[1,0]
	v_pk_fma_f32 v[18:19], v[120:121], v[18:19], v[128:129]
	v_pk_fma_f32 v[20:21], v[122:123], v[20:21], v[130:131]
	v_pk_fma_f32 v[22:23], v[124:125], v[22:23], v[132:133]
	v_pk_fma_f32 v[24:25], v[126:127], v[24:25], v[134:135]
	v_pk_fma_f32 v[18:19], v[18:19], v[136:137], v[112:113]
	v_pk_fma_f32 v[20:21], v[20:21], v[138:139], v[114:115]
	v_pk_fma_f32 v[22:23], v[22:23], v[140:141], v[116:117]
	v_pk_fma_f32 v[24:25], v[24:25], v[142:143], v[118:119]
	v_cvt_pk_bf16_f32 v144, v18, v19
	v_cvt_pk_bf16_f32 v145, v20, v21
	v_cvt_pk_bf16_f32 v146, v22, v23
	v_cvt_pk_bf16_f32 v147, v24, v25
	global_store_dwordx4 v[32:33], v[144:147], off
	v_lshl_add_u64 v[32:33], v[32:33], 0, s[6:7]
	s_waitcnt vmcnt(8)
	v_pk_add_f32 v[18:19], v[214:215], v[242:243] op_sel_hi:[1,0] neg_lo:[0,1] neg_hi:[0,1]
	v_pk_add_f32 v[20:21], v[216:217], v[242:243] op_sel_hi:[1,0] neg_lo:[0,1] neg_hi:[0,1]
	v_pk_add_f32 v[22:23], v[218:219], v[242:243] op_sel_hi:[1,0] neg_lo:[0,1] neg_hi:[0,1]
	v_pk_add_f32 v[24:25], v[220:221], v[242:243] op_sel_hi:[1,0] neg_lo:[0,1] neg_hi:[0,1]
	v_pk_mul_f32 v[18:19], v[242:243], v[18:19] op_sel:[1,0]
	v_pk_mul_f32 v[20:21], v[242:243], v[20:21] op_sel:[1,0]
	v_pk_mul_f32 v[22:23], v[242:243], v[22:23] op_sel:[1,0]
	v_pk_mul_f32 v[24:25], v[242:243], v[24:25] op_sel:[1,0]
	v_pk_fma_f32 v[18:19], v[120:121], v[18:19], v[128:129]
	v_pk_fma_f32 v[20:21], v[122:123], v[20:21], v[130:131]
	v_pk_fma_f32 v[22:23], v[124:125], v[22:23], v[132:133]
	v_pk_fma_f32 v[24:25], v[126:127], v[24:25], v[134:135]
	v_pk_fma_f32 v[18:19], v[18:19], v[136:137], v[112:113]
	v_pk_fma_f32 v[20:21], v[20:21], v[138:139], v[114:115]
	v_pk_fma_f32 v[22:23], v[22:23], v[140:141], v[116:117]
	v_pk_fma_f32 v[24:25], v[24:25], v[142:143], v[118:119]
	v_cvt_pk_bf16_f32 v26, v18, v19
	v_cvt_pk_bf16_f32 v27, v20, v21
	v_cvt_pk_bf16_f32 v28, v22, v23
	v_cvt_pk_bf16_f32 v29, v24, v25
	global_store_dwordx4 v[32:33], v[26:29], off
	v_lshl_add_u64 v[32:33], v[32:33], 0, s[6:7]
	s_waitcnt vmcnt(7)
	v_pk_add_f32 v[18:19], v[222:223], v[244:245] op_sel_hi:[1,0] neg_lo:[0,1] neg_hi:[0,1]
	v_pk_add_f32 v[20:21], v[224:225], v[244:245] op_sel_hi:[1,0] neg_lo:[0,1] neg_hi:[0,1]
	v_pk_add_f32 v[22:23], v[226:227], v[244:245] op_sel_hi:[1,0] neg_lo:[0,1] neg_hi:[0,1]
	v_pk_add_f32 v[24:25], v[228:229], v[244:245] op_sel_hi:[1,0] neg_lo:[0,1] neg_hi:[0,1]
	v_pk_mul_f32 v[18:19], v[244:245], v[18:19] op_sel:[1,0]
	v_pk_mul_f32 v[20:21], v[244:245], v[20:21] op_sel:[1,0]
	v_pk_mul_f32 v[22:23], v[244:245], v[22:23] op_sel:[1,0]
	v_pk_mul_f32 v[24:25], v[244:245], v[24:25] op_sel:[1,0]
	v_pk_fma_f32 v[18:19], v[120:121], v[18:19], v[128:129]
	v_pk_fma_f32 v[20:21], v[122:123], v[20:21], v[130:131]
	v_pk_fma_f32 v[22:23], v[124:125], v[22:23], v[132:133]
	v_pk_fma_f32 v[24:25], v[126:127], v[24:25], v[134:135]
	v_pk_fma_f32 v[18:19], v[18:19], v[136:137], v[112:113]
	v_pk_fma_f32 v[20:21], v[20:21], v[138:139], v[114:115]
	v_pk_fma_f32 v[22:23], v[22:23], v[140:141], v[116:117]
	v_pk_fma_f32 v[24:25], v[24:25], v[142:143], v[118:119]
	v_cvt_pk_bf16_f32 v144, v18, v19
	v_cvt_pk_bf16_f32 v145, v20, v21
	v_cvt_pk_bf16_f32 v146, v22, v23
	v_cvt_pk_bf16_f32 v147, v24, v25
	global_store_dwordx4 v[32:33], v[144:147], off
	s_branch .LBB0_359
.Lfh_l0:
	v_ashrrev_i32_e32 v12, 5, v57
	v_ashrrev_i32_e32 v13, 31, v12
	v_lshl_add_u64 v[16:17], v[12:13], 0, s[96:97]
	v_lshlrev_b64 v[14:15], 12, v[12:13]
	v_lshl_add_u64 v[14:15], v[6:7], 0, v[14:15]
	s_mov_b64 s[6:7], 0x8000
	global_load_dwordx4 v[166:169], v[14:15], off
	global_load_dwordx4 v[170:173], v[14:15], off offset:16
	v_lshl_add_u64 v[14:15], v[14:15], 0, s[6:7]
	global_load_dwordx4 v[174:177], v[14:15], off
	global_load_dwordx4 v[178:181], v[14:15], off offset:16
	v_lshl_add_u64 v[14:15], v[14:15], 0, s[6:7]
	global_load_dwordx4 v[182:185], v[14:15], off
	global_load_dwordx4 v[186:189], v[14:15], off offset:16
	v_lshl_add_u64 v[14:15], v[14:15], 0, s[6:7]
	global_load_dwordx4 v[190:193], v[14:15], off
	global_load_dwordx4 v[194:197], v[14:15], off offset:16
	v_lshl_add_u64 v[14:15], v[14:15], 0, s[6:7]
	global_load_dwordx4 v[198:201], v[14:15], off
	global_load_dwordx4 v[202:205], v[14:15], off offset:16
	v_lshl_add_u64 v[14:15], v[14:15], 0, s[6:7]
	global_load_dwordx4 v[206:209], v[14:15], off
	global_load_dwordx4 v[210:213], v[14:15], off offset:16
	v_lshl_add_u64 v[14:15], v[14:15], 0, s[6:7]
	global_load_dwordx4 v[214:217], v[14:15], off
	global_load_dwordx4 v[218:221], v[14:15], off offset:16
	v_lshl_add_u64 v[14:15], v[14:15], 0, s[6:7]
	global_load_dwordx4 v[222:225], v[14:15], off
	global_load_dwordx4 v[226:229], v[14:15], off offset:16
	v_lshlrev_b64 v[16:17], 10, v[16:17]
	v_lshl_add_u64 v[30:31], v[2:3], 0, v[16:17]
	v_lshl_add_u64 v[32:33], v[0:1], 0, v[16:17]
	v_lshl_add_u64 v[32:33], v[32:33], 0, s[78:79]
	v_cndmask_b32_e64 v33, v33, v31, s[4:5]
	v_cndmask_b32_e64 v32, v32, v30, s[4:5]
	s_mov_b64 s[6:7], 0x2000
	s_waitcnt vmcnt(14)
	v_pk_add_f32 v[136:137], v[104:105], 1.0 op_sel_hi:[1,0]
	v_pk_add_f32 v[138:139], v[106:107], 1.0 op_sel_hi:[1,0]
	v_pk_add_f32 v[140:141], v[108:109], 1.0 op_sel_hi:[1,0]
	v_pk_add_f32 v[142:143], v[110:111], 1.0 op_sel_hi:[1,0]
	v_pk_fma_f32 v[18:19], v[166:167], v[136:137], v[112:113]
	v_pk_fma_f32 v[20:21], v[168:169], v[138:139], v[114:115]
	v_pk_fma_f32 v[22:23], v[170:171], v[140:141], v[116:117]
	v_pk_fma_f32 v[24:25], v[172:173], v[142:143], v[118:119]
	v_cvt_pk_bf16_f32 v26, v18, v19
	v_cvt_pk_bf16_f32 v27, v20, v21
	v_cvt_pk_bf16_f32 v28, v22, v23
	v_cvt_pk_bf16_f32 v29, v24, v25
	global_store_dwordx4 v[32:33], v[26:29], off
	v_lshl_add_u64 v[32:33], v[32:33], 0, s[6:7]
	s_waitcnt vmcnt(13)
	v_pk_fma_f32 v[18:19], v[174:175], v[136:137], v[112:113]
	v_pk_fma_f32 v[20:21], v[176:177], v[138:139], v[114:115]
	v_pk_fma_f32 v[22:23], v[178:179], v[140:141], v[116:117]
	v_pk_fma_f32 v[24:25], v[180:181], v[142:143], v[118:119]
	v_cvt_pk_bf16_f32 v144, v18, v19
	v_cvt_pk_bf16_f32 v145, v20, v21
	v_cvt_pk_bf16_f32 v146, v22, v23
	v_cvt_pk_bf16_f32 v147, v24, v25
	global_store_dwordx4 v[32:33], v[144:147], off
	v_lshl_add_u64 v[32:33], v[32:33], 0, s[6:7]
	s_waitcnt vmcnt(12)
	v_pk_fma_f32 v[18:19], v[182:183], v[136:137], v[112:113]
	v_pk_fma_f32 v[20:21], v[184:185], v[138:139], v[114:115]
	v_pk_fma_f32 v[22:23], v[186:187], v[140:141], v[116:117]
	v_pk_fma_f32 v[24:25], v[188:189], v[142:143], v[118:119]
	v_cvt_pk_bf16_f32 v26, v18, v19
	v_cvt_pk_bf16_f32 v27, v20, v21
	v_cvt_pk_bf16_f32 v28, v22, v23
	v_cvt_pk_bf16_f32 v29, v24, v25
	global_store_dwordx4 v[32:33], v[26:29], off
	v_lshl_add_u64 v[32:33], v[32:33], 0, s[6:7]
	s_waitcnt vmcnt(11)
	v_pk_fma_f32 v[18:19], v[190:191], v[136:137], v[112:113]
	v_pk_fma_f32 v[20:21], v[192:193], v[138:139], v[114:115]
	v_pk_fma_f32 v[22:23], v[194:195], v[140:141], v[116:117]
	v_pk_fma_f32 v[24:25], v[196:197], v[142:143], v[118:119]
	v_cvt_pk_bf16_f32 v144, v18, v19
	v_cvt_pk_bf16_f32 v145, v20, v21
	v_cvt_pk_bf16_f32 v146, v22, v23
	v_cvt_pk_bf16_f32 v147, v24, v25
	global_store_dwordx4 v[32:33], v[144:147], off
	v_lshl_add_u64 v[32:33], v[32:33], 0, s[6:7]
	s_waitcnt vmcnt(10)
	v_pk_fma_f32 v[18:19], v[198:199], v[136:137], v[112:113]
	v_pk_fma_f32 v[20:21], v[200:201], v[138:139], v[114:115]
	v_pk_fma_f32 v[22:23], v[202:203], v[140:141], v[116:117]
	v_pk_fma_f32 v[24:25], v[204:205], v[142:143], v[118:119]
	v_cvt_pk_bf16_f32 v26, v18, v19
	v_cvt_pk_bf16_f32 v27, v20, v21
	v_cvt_pk_bf16_f32 v28, v22, v23
	v_cvt_pk_bf16_f32 v29, v24, v25
	global_store_dwordx4 v[32:33], v[26:29], off
	v_lshl_add_u64 v[32:33], v[32:33], 0, s[6:7]
	s_waitcnt vmcnt(9)
	v_pk_fma_f32 v[18:19], v[206:207], v[136:137], v[112:113]
	v_pk_fma_f32 v[20:21], v[208:209], v[138:139], v[114:115]
	v_pk_fma_f32 v[22:23], v[210:211], v[140:141], v[116:117]
	v_pk_fma_f32 v[24:25], v[212:213], v[142:143], v[118:119]
	v_cvt_pk_bf16_f32 v144, v18, v19
	v_cvt_pk_bf16_f32 v145, v20, v21
	v_cvt_pk_bf16_f32 v146, v22, v23
	v_cvt_pk_bf16_f32 v147, v24, v25
	global_store_dwordx4 v[32:33], v[144:147], off
	v_lshl_add_u64 v[32:33], v[32:33], 0, s[6:7]
	s_waitcnt vmcnt(8)
	v_pk_fma_f32 v[18:19], v[214:215], v[136:137], v[112:113]
	v_pk_fma_f32 v[20:21], v[216:217], v[138:139], v[114:115]
	v_pk_fma_f32 v[22:23], v[218:219], v[140:141], v[116:117]
	v_pk_fma_f32 v[24:25], v[220:221], v[142:143], v[118:119]
	v_cvt_pk_bf16_f32 v26, v18, v19
	v_cvt_pk_bf16_f32 v27, v20, v21
	v_cvt_pk_bf16_f32 v28, v22, v23
	v_cvt_pk_bf16_f32 v29, v24, v25
	global_store_dwordx4 v[32:33], v[26:29], off
	v_lshl_add_u64 v[32:33], v[32:33], 0, s[6:7]
	s_waitcnt vmcnt(7)
	v_pk_fma_f32 v[18:19], v[222:223], v[136:137], v[112:113]
	v_pk_fma_f32 v[20:21], v[224:225], v[138:139], v[114:115]
	v_pk_fma_f32 v[22:23], v[226:227], v[140:141], v[116:117]
	v_pk_fma_f32 v[24:25], v[228:229], v[142:143], v[118:119]
	v_cvt_pk_bf16_f32 v144, v18, v19
	v_cvt_pk_bf16_f32 v145, v20, v21
	v_cvt_pk_bf16_f32 v146, v22, v23
	v_cvt_pk_bf16_f32 v147, v24, v25
	global_store_dwordx4 v[32:33], v[144:147], off
	s_branch .LBB0_359
